# fox2-qk-subtileA-first-fma-under-B-mfma
# baseline (speedup 1.0000x reference)
; #define LAS __attribute__((address_space(3)))
; __device__ __forceinline__ int crow(int r, int hi) { return (r & 3) + 8 * (r >> 2) + 4 * hi; }
; __device__ __forceinline__ void fox_scores(v16f& p0, v16f& p1, const v16f& c0, const v16f& c1, bool diag, int t, int qpos, int hi) {
;     p0 = p0 * C1 - c0; p1 = p1 * C1 - c1;
;     if (diag) {
; #pragma unroll
;         for (int r = 0; r < 16; ++r) { const int kv = 64 * t + crow(r, hi); if (kv > qpos) p0[r] = -INFINITY; if (kv + 32 > qpos) p1[r] = -INFINITY; }
;     }
; __device__ __forceinline__ void fox2_phase(LAS unsigned char* lds, const bf16_t* QKV, const float* CL2, bf16_t* AO) {
;     ...
;                 { v8s kf[8]; k_load(lds + ATT_K + bi * KTB, kf, r32, hi); qk_mma(kf, qa, a0, a1); qk_mma(kf, qb_, b0, b1); }
;                 { v16f c0, c1; const LAS float* kbp = AUXL + bi * 64 + 4 * hi;
; #pragma unroll
;                   for (int g = 0; g < 4; ++g) { const v4f x0 = *(const LAS v4f*)(kbp + 8 * g), x1 = *(const LAS v4f*)(kbp + 32 + 8 * g);
; #pragma unroll
;                       for (int e = 0; e < 4; ++e) { c0[4 * g + e] = x0[e]; c1[4 * g + e] = x1[e]; } }
;                   fox_scores(a0, a1, c0, c1, diag, t, qposA, hi); fox_scores(b0, b1, c0, c1, diag, t, qposB, hi); }
.LBB0_225:
	s_mul_i32 s60, s73, 0x2400
	v_add_u32_e32 v70, s60, v249
	ds_read_b128 v[82:85], v70 offset:4608
	ds_read_b128 v[66:69], v70
	ds_read_b128 v[86:89], v70 offset:32
	ds_read_b128 v[226:229], v70 offset:4640
	ds_read_b128 v[90:93], v70 offset:64
	ds_read_b128 v[230:233], v70 offset:4672
	ds_read_b128 v[94:97], v70 offset:96
	ds_read_b128 v[204:207], v70 offset:4704
	v_lshl_add_u32 v70, s73, 8, v248
	ds_read_b128 v[170:173], v70 offset:52736
	ds_read_b128 v[186:189], v70 offset:52608
	ds_read_b128 v[190:193], v70 offset:52640
	ds_read_b128 v[174:177], v70 offset:52768
	ds_read_b128 v[194:197], v70 offset:52672
	ds_read_b128 v[178:181], v70 offset:52800
	ds_read_b128 v[198:201], v70 offset:52704
	ds_read_b128 v[182:185], v70 offset:52832
	s_waitcnt lgkmcnt(14)
	v_mfma_f32_32x32x16_bf16 v[98:113], v[66:69], v[130:133], 0
	s_waitcnt lgkmcnt(13)
	v_mfma_f32_32x32x16_bf16 v[98:113], v[86:89], v[134:137], v[98:113]
	s_waitcnt lgkmcnt(11)
	v_mfma_f32_32x32x16_bf16 v[98:113], v[90:93], v[146:149], v[98:113]
	s_waitcnt lgkmcnt(9)
	v_mfma_f32_32x32x16_bf16 v[98:113], v[94:97], v[150:153], v[98:113]
	v_mfma_f32_32x32x16_bf16 v[114:129], v[82:85], v[130:133], 0
	v_mfma_f32_32x32x16_bf16 v[114:129], v[226:229], v[134:137], v[114:129]
	v_mfma_f32_32x32x16_bf16 v[114:129], v[230:233], v[146:149], v[114:129]
	s_waitcnt lgkmcnt(8)
	v_mfma_f32_32x32x16_bf16 v[114:129], v[204:207], v[150:153], v[114:129]
	v_mfma_f32_32x32x16_bf16 v[66:81], v[66:69], v[138:141], 0
	s_cmp_eq_u32 s68, s72
	s_cselect_b64 vcc, -1, 0
	s_cmp_lg_u32 s68, s72
	v_mfma_f32_32x32x16_bf16 v[66:81], v[86:89], v[142:145], v[66:81]
	s_waitcnt lgkmcnt(0)
	s_nop 2
	v_fma_f32 v112, v112, s52, v200
	v_fma_f32 v113, v113, s52, v201
	v_fma_f32 v108, v108, s52, v196
	v_fma_f32 v109, v109, s52, v197
	v_fma_f32 v104, v104, s52, v192
	v_fma_f32 v105, v105, s52, v193
	v_mfma_f32_32x32x16_bf16 v[66:81], v[90:93], v[154:157], v[66:81]
	v_pk_fma_f32 v[100:101], v[100:101], s[52:53], v[188:189] op_sel_hi:[1,0,1]
	v_pk_fma_f32 v[98:99], v[98:99], s[52:53], v[186:187] op_sel_hi:[1,0,1]
	v_pk_fma_f32 v[110:111], v[110:111], s[52:53], v[198:199] op_sel_hi:[1,0,1]
	v_pk_fma_f32 v[106:107], v[106:107], s[52:53], v[194:195] op_sel_hi:[1,0,1]
	v_fma_f32 v102, v102, s52, v190
	v_fma_f32 v103, v103, s52, v191
	v_mfma_f32_32x32x16_bf16 v[66:81], v[94:97], v[158:161], v[66:81]
	v_fma_f32 v128, v128, s52, v184
	v_fma_f32 v129, v129, s52, v185
	v_fma_f32 v124, v124, s52, v180
	v_fma_f32 v125, v125, s52, v181
	v_mfma_f32_32x32x16_bf16 v[82:97], v[82:85], v[138:141], 0
	v_fma_f32 v120, v120, s52, v176
	v_fma_f32 v121, v121, s52, v177
	v_pk_fma_f32 v[116:117], v[116:117], s[52:53], v[172:173] op_sel_hi:[1,0,1]
	v_pk_fma_f32 v[114:115], v[114:115], s[52:53], v[170:171] op_sel_hi:[1,0,1]
	v_mfma_f32_32x32x16_bf16 v[82:97], v[226:229], v[142:145], v[82:97]
	v_mov_b32_e32 v227, v177
	v_mov_b32_e32 v226, v176
	v_mov_b32_e32 v229, v173
	v_mov_b32_e32 v228, v172
	v_mfma_f32_32x32x16_bf16 v[82:97], v[230:233], v[154:157], v[82:97]
	v_mov_b32_e32 v231, v185
	v_mov_b32_e32 v230, v184
	v_mov_b32_e32 v233, v181
	v_mov_b32_e32 v232, v180
	v_mfma_f32_32x32x16_bf16 v[82:97], v[204:207], v[158:161], v[82:97]
	v_pk_fma_f32 v[126:127], v[126:127], s[52:53], v[182:183] op_sel_hi:[1,0,1]
	v_pk_fma_f32 v[122:123], v[122:123], s[52:53], v[178:179] op_sel_hi:[1,0,1]
	v_pk_fma_f32 v[118:119], v[118:119], s[52:53], v[174:175] op_sel_hi:[1,0,1]
	s_cbranch_scc1 .LBB0_229
	v_readlane_b32 s60, v255, 19
	v_readlane_b32 s61, v255, 20
	v_cndmask_b32_e64 v124, v124, v241, s[84:85]
	v_cndmask_b32_e64 v125, v125, v241, s[88:89]
	v_cndmask_b32_e64 v114, v114, v241, s[60:61]
	v_readlane_b32 s60, v255, 21
	v_readlane_b32 s61, v255, 22
	v_cndmask_b32_e64 v126, v126, v241, s[92:93]
	v_cndmask_b32_e64 v127, v127, v241, s[96:97]
	v_cndmask_b32_e64 v115, v115, v241, s[60:61]
	v_readlane_b32 s60, v255, 23
	v_readlane_b32 s61, v255, 24
	v_cndmask_b32_e64 v128, v128, v241, s[6:7]
	s_nop 0
	v_cndmask_b32_e64 v116, v116, v241, s[60:61]
	v_readlane_b32 s60, v255, 25
	v_readlane_b32 s61, v255, 26
	s_nop 1
	v_cndmask_b32_e64 v117, v117, v241, s[60:61]
	v_readlane_b32 s60, v255, 27
	v_readlane_b32 s61, v255, 28
	s_nop 1
	v_cndmask_b32_e64 v118, v118, v241, s[60:61]
	v_readlane_b32 s60, v255, 29
	v_readlane_b32 s61, v255, 30
	s_nop 1
	v_cndmask_b32_e64 v119, v119, v241, s[60:61]
	v_readlane_b32 s60, v255, 31
	v_readlane_b32 s61, v255, 32
	s_nop 1
	v_cndmask_b32_e64 v120, v120, v241, s[60:61]
	v_readlane_b32 s60, v255, 33
	v_readlane_b32 s61, v255, 34
	s_nop 1
	v_cndmask_b32_e64 v121, v121, v241, s[60:61]
	v_readlane_b32 s60, v255, 35
	v_readlane_b32 s61, v255, 36
	s_nop 1
	v_cndmask_b32_e64 v122, v122, v241, s[60:61]
	v_readlane_b32 s60, v255, 37
	v_readlane_b32 s61, v255, 38
	s_nop 1
	v_cndmask_b32_e64 v123, v123, v241, s[60:61]
	s_and_saveexec_b64 s[60:61], s[10:11]
	v_mov_b32_e32 v129, s80
	s_or_b64 exec, exec, s[60:61]
	v_cndmask_b32_e64 v172, v98, v241, s[42:43]
	v_cndmask_b32_e64 v99, v241, v99, s[46:47]
	v_cndmask_b32_e64 v98, v172, v98, s[46:47]
	v_cndmask_b32_e64 v100, v100, v241, s[50:51]
	v_cndmask_b32_e64 v101, v101, v241, s[54:55]
	v_cndmask_b32_e64 v102, v102, v241, s[58:59]
	v_cndmask_b32_e64 v103, v103, v241, s[62:63]
	v_cndmask_b32_e64 v104, v104, v241, s[66:67]
	v_cndmask_b32_e64 v105, v105, v241, s[70:71]
	v_cndmask_b32_e64 v106, v106, v241, s[74:75]
	v_cndmask_b32_e64 v107, v107, v241, s[78:79]
	v_cndmask_b32_e64 v108, v108, v241, s[82:83]
	v_cndmask_b32_e64 v109, v109, v241, s[86:87]
	v_cndmask_b32_e64 v110, v110, v241, s[90:91]
	v_cndmask_b32_e64 v111, v111, v241, s[94:95]
	v_cndmask_b32_e64 v112, v112, v241, s[4:5]
	v_cndmask_b32_e64 v113, v113, v241, s[8:9]
; #define LAS __attribute__((address_space(3)))
; __device__ __forceinline__ int crow(int r, int hi) { return (r & 3) + 8 * (r >> 2) + 4 * hi; }
; __device__ __forceinline__ void fox_scores(v16f& p0, v16f& p1, const v16f& c0, const v16f& c1, bool diag, int t, int qpos, int hi) {
;     p0 = p0 * C1 - c0; p1 = p1 * C1 - c1;
;     if (diag) {
; #pragma unroll
;         for (int r = 0; r < 16; ++r) { const int kv = 64 * t + crow(r, hi); if (kv > qpos) p0[r] = -INFINITY; if (kv + 32 > qpos) p1[r] = -INFINITY; }
;     }
; __device__ __forceinline__ void fox2_phase(LAS unsigned char* lds, const bf16_t* QKV, const float* CL2, bf16_t* AO) {
;     ...
;                 { v8s kf[8]; k_load(lds + ATT_K + bi * KTB, kf, r32, hi); qk_mma(kf, qa, a0, a1); qk_mma(kf, qb_, b0, b1); }
;                 { v16f c0, c1; const LAS float* kbp = AUXL + bi * 64 + 4 * hi;
; #pragma unroll
;                   for (int g = 0; g < 4; ++g) { const v4f x0 = *(const LAS v4f*)(kbp + 8 * g), x1 = *(const LAS v4f*)(kbp + 32 + 8 * g);
; #pragma unroll
;                       for (int e = 0; e < 4; ++e) { c0[4 * g + e] = x0[e]; c1[4 * g + e] = x1[e]; } }
;                   fox_scores(a0, a1, c0, c1, diag, t, qposA, hi); fox_scores(b0, b1, c0, c1, diag, t, qposB, hi); }
.LBB0_229:
	v_pk_fma_f32 v[176:177], v[66:67], s[52:53], v[186:187] op_sel_hi:[1,0,1]
	v_pk_fma_f32 v[78:79], v[78:79], s[52:53], v[198:199] op_sel_hi:[1,0,1]
	v_pk_fma_f32 v[74:75], v[74:75], s[52:53], v[194:195] op_sel_hi:[1,0,1]
	v_pk_fma_f32 v[172:173], v[72:73], s[52:53], v[192:193] op_sel_hi:[1,0,1]
	v_pk_fma_f32 v[80:81], v[80:81], s[52:53], v[200:201] op_sel_hi:[1,0,1]
	v_pk_fma_f32 v[76:77], v[76:77], s[52:53], v[196:197] op_sel_hi:[1,0,1]
	v_pk_fma_f32 v[180:181], v[70:71], s[52:53], v[190:191] op_sel_hi:[1,0,1]
	v_pk_fma_f32 v[184:185], v[68:69], s[52:53], v[188:189] op_sel_hi:[1,0,1]
	s_andn2_b64 vcc, exec, vcc
	v_pk_fma_f32 v[94:95], v[94:95], s[52:53], v[182:183] op_sel_hi:[1,0,1]
	v_pk_fma_f32 v[90:91], v[90:91], s[52:53], v[178:179] op_sel_hi:[1,0,1]
	v_pk_fma_f32 v[96:97], v[96:97], s[52:53], v[230:231] op_sel_hi:[1,0,1]
	v_pk_fma_f32 v[92:93], v[92:93], s[52:53], v[232:233] op_sel_hi:[1,0,1]
	v_pk_fma_f32 v[70:71], v[88:89], s[52:53], v[226:227] op_sel_hi:[1,0,1]
	v_pk_fma_f32 v[72:73], v[86:87], s[52:53], v[174:175] op_sel_hi:[1,0,1]
	v_pk_fma_f32 v[66:67], v[84:85], s[52:53], v[228:229] op_sel_hi:[1,0,1]
	v_pk_fma_f32 v[68:69], v[82:83], s[52:53], v[170:171] op_sel_hi:[1,0,1]
	s_cbranch_vccnz .LBB0_233
	v_cndmask_b32_e64 v82, v68, v241, s[42:43]
	v_cndmask_b32_e64 v69, v241, v69, s[46:47]
	v_cndmask_b32_e64 v68, v82, v68, s[46:47]
	v_cndmask_b32_e64 v66, v66, v241, s[50:51]
	v_cndmask_b32_e64 v67, v67, v241, s[54:55]
	v_cndmask_b32_e64 v72, v72, v241, s[58:59]
	v_cndmask_b32_e64 v73, v73, v241, s[62:63]
	v_cndmask_b32_e64 v70, v70, v241, s[66:67]
	v_cndmask_b32_e64 v71, v71, v241, s[70:71]
	v_cndmask_b32_e64 v90, v90, v241, s[74:75]
	v_cndmask_b32_e64 v91, v91, v241, s[78:79]
	v_cndmask_b32_e64 v92, v92, v241, s[82:83]
	v_cndmask_b32_e64 v93, v93, v241, s[86:87]
	v_cndmask_b32_e64 v94, v94, v241, s[90:91]
	v_cndmask_b32_e64 v95, v95, v241, s[94:95]
	v_cndmask_b32_e64 v96, v96, v241, s[4:5]
	s_and_saveexec_b64 s[60:61], s[8:9]
	v_mov_b32_e32 v97, s80
	s_or_b64 exec, exec, s[60:61]
	v_cndmask_b32_e64 v82, v176, v241, s[12:13]
	v_cndmask_b32_e64 v177, v241, v177, s[14:15]
	v_cndmask_b32_e64 v176, v82, v176, s[14:15]
	v_cndmask_b32_e64 v184, v184, v241, s[16:17]
	v_cndmask_b32_e64 v185, v185, v241, s[18:19]
	v_cndmask_b32_e64 v180, v180, v241, s[20:21]
	v_cndmask_b32_e64 v181, v181, v241, s[22:23]
	v_cndmask_b32_e64 v172, v172, v241, s[24:25]
	v_cndmask_b32_e64 v173, v173, v241, s[26:27]
	v_cndmask_b32_e64 v74, v74, v241, s[28:29]
	v_cndmask_b32_e64 v75, v75, v241, s[30:31]
	v_cndmask_b32_e64 v76, v76, v241, s[34:35]
	v_cndmask_b32_e64 v77, v77, v241, s[36:37]
	v_cndmask_b32_e64 v78, v78, v241, s[48:49]
	v_cndmask_b32_e64 v79, v79, v241, s[38:39]
	v_cndmask_b32_e64 v80, v80, v241, s[44:45]
	v_cndmask_b32_e64 v81, v81, v241, s[0:1]
